# prologue weight transposes: nt on the f32 weight loads and on the bf16 transposed weight stores (write-once, read much later)
# speedup vs baseline: 1.0006x; 1.0006x over previous
; #define LAS __attribute__((address_space(3)))
; __device__ __forceinline__ unsigned pk2(float lo, float hi) { f32x2 v = {lo, hi}; bf16x2_t b = __builtin_convertvector(v, bf16x2_t); return __builtin_bit_cast(unsigned, b); }
; #define LDS_WAIT() asm volatile("s_waitcnt lgkmcnt(0)" ::: "memory")
; template <class MAP>
; __device__ __forceinline__ void transpose_item(const float* W, int ldw, int K, bf16_t* WT, int k0, int nd0, LAS float* scr, int lane, const MAP& map) {
;     const int nq = 4 * (lane & 15), ns = map(nd0 + nq), kr = lane >> 4;
;     f32x4 v[16];
; #pragma unroll
;     for (int i = 0; i < 16; ++i) v[i] = ns >= 0 ? *(const f32x4*)(W + (size_t)(k0 + 4 * i + kr) * ldw + ns) : (f32x4){0.f, 0.f, 0.f, 0.f};
; #pragma unroll
;     for (int i = 0; i < 16; ++i) { LAS float* d = scr + (4 * i + kr) * 65 + nq; d[0] = v[i].x; d[1] = v[i].y; d[2] = v[i].z; d[3] = v[i].w; }
;     LDS_WAIT(); asm volatile("" ::: "memory");
;     const int c = lane & 7;
; #pragma unroll
;     for (int j = 0; j < 8; ++j) { const int n = (lane >> 3) + 8 * j; const LAS float* s = scr + (8 * c) * 65 + n;
;         u32x4 o; o.x = pk2(s[0 * 65], s[1 * 65]); o.y = pk2(s[2 * 65], s[3 * 65]); o.z = pk2(s[4 * 65], s[5 * 65]); o.w = pk2(s[6 * 65], s[7 * 65]);
;         *(u32x4*)(WT + (size_t)(nd0 + n) * K + k0 + 8 * c) = o; }
;     LDS_WAIT(); asm volatile("" ::: "memory");
.LBB0_12:
	s_mul_hi_i32 s4, s61, 0x342da7f3
	s_lshr_b32 s5, s4, 31
	s_ashr_i32 s4, s4, 11
	s_add_i32 s8, s4, s5
	s_mul_i32 s4, s8, 0xffffd8c0
	s_add_i32 s10, s61, s4
	s_cmpk_gt_i32 s10, 0x1b7f
	s_mov_b64 s[4:5], -1
	s_cbranch_scc0 .LBB0_30
	s_cmpk_gt_u32 s10, 0x1c7f
	s_cbranch_scc0 .LBB0_27
	s_cmpk_gt_u32 s10, 0x227f
	s_cbranch_scc0 .LBB0_24
	s_cmpk_gt_u32 s10, 0x267f
	s_cbranch_scc0 .LBB0_21
	s_cmpk_gt_u32 s10, 0x26bf
	s_cbranch_scc0 .LBB0_18
	s_load_dwordx2 s[4:5], s[0:1], 0x68
	s_ashr_i32 s9, s8, 31
	s_add_i32 s6, s10, 0xffffd940
	s_lshl_b64 s[62:63], s[8:9], 21
	v_mov_b32_e32 v95, v73
	s_waitcnt lgkmcnt(0)
	s_add_u32 s11, s4, s62
	s_addc_u32 s62, s5, s63
	s_lshl_b64 s[4:5], s[6:7], 14
	s_add_u32 s4, s11, s4
	s_addc_u32 s5, s62, s5
	v_lshl_add_u64 v[2:3], s[4:5], 0, v[94:95]
	v_lshl_add_u64 v[50:51], v[2:3], 0, v[74:75]
	v_add_co_u32_e32 v46, vcc, s35, v50
	global_load_dwordx4 v[2:5], v[50:51], off nt
	global_load_dwordx4 v[6:9], v[50:51], off offset:1024 nt
	global_load_dwordx4 v[10:13], v[50:51], off offset:2048 nt
	global_load_dwordx4 v[14:17], v[50:51], off offset:3072 nt
	v_addc_co_u32_e32 v47, vcc, 0, v51, vcc
	v_add_co_u32_e32 v30, vcc, s34, v50
	global_load_dwordx4 v[18:21], v[46:47], off offset:-4096 nt
	s_nop 0
	v_addc_co_u32_e32 v31, vcc, 0, v51, vcc
	v_add_co_u32_e32 v62, vcc, s36, v50
	global_load_dwordx4 v[22:25], v[30:31], off offset:1024 nt
	global_load_dwordx4 v[26:29], v[30:31], off offset:2048 nt
	s_nop 0
	global_load_dwordx4 v[30:33], v[30:31], off offset:3072 nt
	s_nop 0
	global_load_dwordx4 v[34:37], v[46:47], off nt
	global_load_dwordx4 v[38:41], v[46:47], off offset:1024 nt
	global_load_dwordx4 v[42:45], v[46:47], off offset:2048 nt
	s_nop 0
	global_load_dwordx4 v[46:49], v[46:47], off offset:3072 nt
	v_addc_co_u32_e32 v63, vcc, 0, v51, vcc
	global_load_dwordx4 v[50:53], v[62:63], off nt
	global_load_dwordx4 v[54:57], v[62:63], off offset:1024 nt
	global_load_dwordx4 v[58:61], v[62:63], off offset:2048 nt
	s_nop 0
	global_load_dwordx4 v[62:65], v[62:63], off offset:3072 nt
	v_add_u32_e32 v95, 0x30c0, v69
	v_add_u32_e32 v96, 0x30c8, v69
	v_add_u32_e32 v97, 0x34d0, v69
	v_add_u32_e32 v142, 0x34d8, v69
	v_add_u32_e32 v143, 0x38e0, v69
	v_add_u32_e32 v144, 0x38e8, v69
	v_add_u32_e32 v145, 0x3cf0, v69
	v_add_u32_e32 v146, 0x3cf8, v69
	s_lshl_b64 s[4:5], s[8:9], 20
	v_add_u32_e32 v147, 0x400, v77
	s_add_u32 s9, s12, s4
	s_addc_u32 s11, s13, s5
	s_lshl_b64 s[4:5], s[6:7], 13
	s_add_u32 s4, s9, s4
	v_lshlrev_b32_e32 v72, 1, v76
	s_addc_u32 s5, s11, s5
	s_waitcnt vmcnt(15)
	ds_write2_b32 v69, v2, v3 offset1:1
	ds_write2_b32 v69, v4, v5 offset0:2 offset1:3
	s_waitcnt vmcnt(14)
	ds_write2_b32 v105, v6, v7 offset1:1
	ds_write2_b32 v106, v8, v9 offset1:1
	s_waitcnt vmcnt(13)
	ds_write2_b32 v107, v10, v11 offset1:1
	ds_write2_b32 v108, v12, v13 offset1:1
	s_waitcnt vmcnt(12)
	ds_write2_b32 v109, v14, v15 offset1:1
	ds_write2_b32 v110, v16, v17 offset1:1
	s_waitcnt vmcnt(11)
	ds_write2_b32 v111, v18, v19 offset1:1
	ds_write2_b32 v112, v20, v21 offset1:1
	s_waitcnt vmcnt(10)
	ds_write2_b32 v113, v22, v23 offset1:1
	ds_write2_b32 v114, v24, v25 offset1:1
	s_waitcnt vmcnt(9)
	ds_write2_b32 v115, v26, v27 offset1:1
	ds_write2_b32 v116, v28, v29 offset1:1
	s_waitcnt vmcnt(8)
	ds_write2_b32 v117, v30, v31 offset1:1
	ds_write2_b32 v118, v32, v33 offset1:1
	s_waitcnt vmcnt(7)
	ds_write2_b32 v119, v34, v35 offset1:1
	ds_write2_b32 v120, v36, v37 offset1:1
	s_waitcnt vmcnt(6)
	ds_write2_b32 v121, v38, v39 offset1:1
	ds_write2_b32 v122, v40, v41 offset1:1
	s_waitcnt vmcnt(5)
	ds_write2_b32 v123, v42, v43 offset1:1
	ds_write2_b32 v124, v44, v45 offset1:1
	s_waitcnt vmcnt(4)
	ds_write2_b32 v125, v46, v47 offset1:1
	ds_write2_b32 v126, v48, v49 offset1:1
	s_waitcnt vmcnt(3)
	ds_write2_b32 v95, v50, v51 offset1:1
	ds_write2_b32 v96, v52, v53 offset1:1
	s_waitcnt vmcnt(2)
	ds_write2_b32 v97, v54, v55 offset1:1
	ds_write2_b32 v142, v56, v57 offset1:1
	s_waitcnt vmcnt(1)
	ds_write2_b32 v143, v58, v59 offset1:1
	ds_write2_b32 v144, v60, v61 offset1:1
	s_waitcnt vmcnt(0)
	ds_write2_b32 v145, v62, v63 offset1:1
	ds_write2_b32 v146, v64, v65 offset1:1
	s_waitcnt lgkmcnt(0)
	ds_read2_b32 v[6:7], v77 offset0:65 offset1:73
	ds_read2_b32 v[8:9], v77 offset1:8
	ds_read2_b32 v[10:11], v77 offset0:130 offset1:138
	ds_read2_b32 v[12:13], v77 offset0:195 offset1:203
	ds_read2_b32 v[14:15], v147 offset0:4 offset1:12
	ds_read2_b32 v[16:17], v147 offset0:69 offset1:77
	ds_read2_b32 v[18:19], v147 offset0:134 offset1:142
	ds_read2_b32 v[20:21], v147 offset0:199 offset1:207
	v_lshl_add_u64 v[22:23], s[4:5], 0, v[72:73]
	s_waitcnt lgkmcnt(6)
	v_cvt_pk_bf16_f32 v2, v8, v6
	s_waitcnt lgkmcnt(4)
	v_cvt_pk_bf16_f32 v3, v10, v12
	s_waitcnt lgkmcnt(2)
	v_cvt_pk_bf16_f32 v4, v14, v16
	s_waitcnt lgkmcnt(0)
	v_cvt_pk_bf16_f32 v5, v18, v20
	v_lshl_add_u64 v[24:25], v[22:23], 0, v[78:79]
	global_store_dwordx4 v[24:25], v[2:5], off nt
	s_mov_b64 s[4:5], 0
	s_nop 0
	v_cvt_pk_bf16_f32 v2, v9, v7
	v_cvt_pk_bf16_f32 v3, v11, v13
	v_cvt_pk_bf16_f32 v4, v15, v17
	v_cvt_pk_bf16_f32 v5, v19, v21
	ds_read2_b32 v[8:9], v77 offset0:81 offset1:89
	ds_read2_b32 v[10:11], v77 offset0:16 offset1:24
	ds_read2_b32 v[12:13], v77 offset0:146 offset1:154
	ds_read2_b32 v[14:15], v77 offset0:211 offset1:219
	ds_read2_b32 v[16:17], v147 offset0:20 offset1:28
	ds_read2_b32 v[18:19], v147 offset0:85 offset1:93
	ds_read2_b32 v[20:21], v147 offset0:150 offset1:158
	ds_read2_b32 v[24:25], v147 offset0:215 offset1:223
	v_lshl_add_u64 v[6:7], v[22:23], 0, v[80:81]
	global_store_dwordx4 v[6:7], v[2:5], off nt
	v_lshl_add_u64 v[6:7], v[22:23], 0, v[82:83]
	s_waitcnt lgkmcnt(6)
; #define LAS __attribute__((address_space(3)))
; __device__ __forceinline__ unsigned pk2(float lo, float hi) { f32x2 v = {lo, hi}; bf16x2_t b = __builtin_convertvector(v, bf16x2_t); return __builtin_bit_cast(unsigned, b); }
; #define LDS_WAIT() asm volatile("s_waitcnt lgkmcnt(0)" ::: "memory")
; #define FIN(i) ((const float*)(const GAS float*)(((const float* const __attribute__((address_space(4)))*)__builtin_amdgcn_kernarg_segment_ptr())[i]))
; template <class MAP>
; __device__ __forceinline__ void transpose_item(const float* W, int ldw, int K, bf16_t* WT, int k0, int nd0, LAS float* scr, int lane, const MAP& map) {
;     ...
;     for (int i = 0; i < 16; ++i) v[i] = ns >= 0 ? *(const f32x4*)(W + (size_t)(k0 + 4 * i + kr) * ldw + ns) : (f32x4){0.f, 0.f, 0.f, 0.f};
; #pragma unroll
;     for (int i = 0; i < 16; ++i) { LAS float* d = scr + (4 * i + kr) * 65 + nq; d[0] = v[i].x; d[1] = v[i].y; d[2] = v[i].z; d[3] = v[i].w; }
;     LDS_WAIT(); asm volatile("" ::: "memory");
;     const int c = lane & 7;
; #pragma unroll
;     for (int j = 0; j < 8; ++j) { const int n = (lane >> 3) + 8 * j; const LAS float* s = scr + (8 * c) * 65 + n;
;         u32x4 o; o.x = pk2(s[0 * 65], s[1 * 65]); o.y = pk2(s[2 * 65], s[3 * 65]); o.z = pk2(s[4 * 65], s[5 * 65]); o.w = pk2(s[6 * 65], s[7 * 65]);
;         *(u32x4*)(WT + (size_t)(nd0 + n) * K + k0 + 8 * c) = o; }
; __device__ __forceinline__ void phase_prologue(Frame& F) {
;     ...
;         if (r < 4 * I_POOL) { const int z = r / I_POOL, rr = r % I_POOL, kb = rr / 4, nb = rr % 4;
;             transpose_item(FIN(IN_WPOOL) + ((size_t)l * 4 + z) * 65536, 256, 256, (bf16_t*)(F.ws + WS_WPOOL + l * al1m(SZ_WPOOL)) + (size_t)z * 65536, 64 * kb, 64 * nb, scr, lane, MapId()); continue; } r -= 4 * I_POOL;
	v_cvt_pk_bf16_f32 v2, v10, v8
	s_waitcnt lgkmcnt(4)
	v_cvt_pk_bf16_f32 v3, v12, v14
	s_waitcnt lgkmcnt(2)
	v_cvt_pk_bf16_f32 v4, v16, v18
	s_waitcnt lgkmcnt(0)
	v_cvt_pk_bf16_f32 v5, v20, v24
	global_store_dwordx4 v[6:7], v[2:5], off nt
	v_lshl_add_u64 v[6:7], v[22:23], 0, v[84:85]
	s_nop 0
	v_cvt_pk_bf16_f32 v2, v11, v9
	v_cvt_pk_bf16_f32 v3, v13, v15
	v_cvt_pk_bf16_f32 v4, v17, v19
	v_cvt_pk_bf16_f32 v5, v21, v25
	ds_read2_b32 v[8:9], v77 offset0:32 offset1:40
	ds_read2_b32 v[10:11], v77 offset0:97 offset1:105
	ds_read2_b32 v[12:13], v77 offset0:162 offset1:170
	ds_read2_b32 v[14:15], v77 offset0:227 offset1:235
	ds_read2_b32 v[16:17], v147 offset0:36 offset1:44
	ds_read2_b32 v[18:19], v147 offset0:101 offset1:109
	ds_read2_b32 v[20:21], v147 offset0:166 offset1:174
	ds_read2_b32 v[24:25], v147 offset0:231 offset1:239
	global_store_dwordx4 v[6:7], v[2:5], off nt
	v_lshl_add_u64 v[6:7], v[22:23], 0, v[86:87]
	s_waitcnt lgkmcnt(6)
	v_cvt_pk_bf16_f32 v2, v8, v10
	s_waitcnt lgkmcnt(4)
	v_cvt_pk_bf16_f32 v3, v12, v14
	s_waitcnt lgkmcnt(2)
	v_cvt_pk_bf16_f32 v4, v16, v18
	s_waitcnt lgkmcnt(0)
	v_cvt_pk_bf16_f32 v5, v20, v24
	global_store_dwordx4 v[6:7], v[2:5], off nt
	v_lshl_add_u64 v[6:7], v[22:23], 0, v[88:89]
	s_nop 0
	v_cvt_pk_bf16_f32 v2, v9, v11
	v_cvt_pk_bf16_f32 v3, v13, v15
	v_cvt_pk_bf16_f32 v4, v17, v19
	v_cvt_pk_bf16_f32 v5, v21, v25
	ds_read2_b32 v[8:9], v77 offset0:48 offset1:56
	ds_read2_b32 v[10:11], v77 offset0:113 offset1:121
	ds_read2_b32 v[12:13], v77 offset0:178 offset1:186
	ds_read2_b32 v[14:15], v77 offset0:243 offset1:251
	ds_read2_b32 v[16:17], v147 offset0:52 offset1:60
	ds_read2_b32 v[18:19], v147 offset0:117 offset1:125
	ds_read2_b32 v[20:21], v147 offset0:182 offset1:190
	ds_read2_b32 v[24:25], v147 offset0:247 offset1:255
	global_store_dwordx4 v[6:7], v[2:5], off nt
	v_lshl_add_u64 v[6:7], v[22:23], 0, v[90:91]
	s_waitcnt lgkmcnt(6)
	v_cvt_pk_bf16_f32 v2, v8, v10
	s_waitcnt lgkmcnt(4)
	v_cvt_pk_bf16_f32 v3, v12, v14
	s_waitcnt lgkmcnt(2)
	v_cvt_pk_bf16_f32 v4, v16, v18
	s_waitcnt lgkmcnt(0)
	v_cvt_pk_bf16_f32 v5, v20, v24
	global_store_dwordx4 v[6:7], v[2:5], off nt
	v_lshl_add_u64 v[6:7], v[22:23], 0, v[92:93]
	s_nop 0
	v_cvt_pk_bf16_f32 v2, v9, v11
	v_cvt_pk_bf16_f32 v3, v13, v15
	v_cvt_pk_bf16_f32 v4, v17, v19
	v_cvt_pk_bf16_f32 v5, v21, v25
	global_store_dwordx4 v[6:7], v[2:5], off nt
	s_waitcnt lgkmcnt(0)
.LBB0_18:
	s_andn2_b64 vcc, exec, s[4:5]
	s_cbranch_vccnz .LBB0_20
	s_load_dwordx2 s[4:5], s[0:1], 0x50
	s_add_i32 s6, s10, 0xffffd980
	s_ashr_i32 s9, s8, 31
	s_lshr_b32 s6, s6, 4
	s_lshl_b64 s[62:63], s[8:9], 20
	s_waitcnt lgkmcnt(0)
	s_add_u32 s9, s4, s62
	s_addc_u32 s11, s5, s63
	s_lshl_b64 s[4:5], s[6:7], 18
	s_add_u32 s64, s9, s4
	s_addc_u32 s65, s11, s5
	s_add_u32 s9, s15, s62
	s_addc_u32 s11, s16, s63
	s_lshl_b64 s[4:5], s[6:7], 17
	s_add_u32 s6, s9, s4
	s_addc_u32 s5, s11, s5
	s_and_b32 s4, s25, 0xc0
	s_and_b32 s9, s31, 0xc0
	v_or_b32_e32 v2, s4, v70
	v_or_b32_e32 v4, s9, v67
	v_lshlrev_b32_e32 v72, 2, v2
	v_lshl_add_u64 v[2:3], s[64:65], 0, v[72:73]
	v_lshlrev_b32_e32 v72, 10, v4
	v_lshl_add_u64 v[62:63], v[2:3], 0, v[72:73]
	v_add_co_u32_e32 v10, vcc, s35, v62
	global_load_dwordx4 v[2:5], v[62:63], off nt
	s_nop 0
	v_addc_co_u32_e32 v11, vcc, 0, v63, vcc
	v_add_co_u32_e32 v18, vcc, s37, v62
	global_load_dwordx4 v[6:9], v[10:11], off offset:-4096 nt
	s_nop 0
	global_load_dwordx4 v[10:13], v[10:11], off nt
	v_addc_co_u32_e32 v19, vcc, 0, v63, vcc
	v_add_co_u32_e32 v26, vcc, s38, v62
	global_load_dwordx4 v[14:17], v[18:19], off offset:-4096 nt
	s_nop 0
	global_load_dwordx4 v[18:21], v[18:19], off nt
	v_addc_co_u32_e32 v27, vcc, 0, v63, vcc
	v_add_co_u32_e32 v34, vcc, s39, v62
	global_load_dwordx4 v[22:25], v[26:27], off offset:-4096 nt
	s_nop 0
	global_load_dwordx4 v[26:29], v[26:27], off nt
	v_addc_co_u32_e32 v35, vcc, 0, v63, vcc
	v_add_co_u32_e32 v42, vcc, s40, v62
	global_load_dwordx4 v[30:33], v[34:35], off offset:-4096 nt
	s_nop 0
	global_load_dwordx4 v[34:37], v[34:35], off nt
	v_addc_co_u32_e32 v43, vcc, 0, v63, vcc
	v_add_co_u32_e32 v50, vcc, s41, v62
	global_load_dwordx4 v[38:41], v[42:43], off offset:-4096 nt
	s_nop 0
	global_load_dwordx4 v[42:45], v[42:43], off nt
	v_addc_co_u32_e32 v51, vcc, 0, v63, vcc
	global_load_dwordx4 v[46:49], v[50:51], off offset:-4096 nt
	s_nop 0
	global_load_dwordx4 v[50:53], v[50:51], off nt
	v_add_co_u32_e32 v58, vcc, s42, v62
	v_add_u32_e32 v72, 0x30c0, v69
	s_nop 0
	v_addc_co_u32_e32 v59, vcc, 0, v63, vcc
	global_load_dwordx4 v[54:57], v[58:59], off offset:-4096 nt
	s_nop 0
	global_load_dwordx4 v[58:61], v[58:59], off nt
	v_add_co_u32_e32 v62, vcc, s43, v62
	v_add_u32_e32 v95, 0x30c8, v69
	s_nop 0
	v_addc_co_u32_e32 v63, vcc, 0, v63, vcc
	global_load_dwordx4 v[62:65], v[62:63], off nt
	s_lshl_b32 s9, s9, 1
	s_add_u32 s62, s6, s9
	s_addc_u32 s63, s5, 0
	s_waitcnt vmcnt(15)
	ds_write2_b32 v69, v2, v3 offset1:1
	ds_write2_b32 v69, v4, v5 offset0:2 offset1:3
	s_waitcnt vmcnt(14)
	ds_write2_b32 v105, v6, v7 offset1:1
	ds_write2_b32 v106, v8, v9 offset1:1
	s_waitcnt vmcnt(13)
	ds_write2_b32 v107, v10, v11 offset1:1
	ds_write2_b32 v108, v12, v13 offset1:1
	s_waitcnt vmcnt(12)
	ds_write2_b32 v109, v14, v15 offset1:1
	ds_write2_b32 v110, v16, v17 offset1:1
	s_waitcnt vmcnt(11)
	ds_write2_b32 v111, v18, v19 offset1:1
	ds_write2_b32 v112, v20, v21 offset1:1
	s_waitcnt vmcnt(10)
	ds_write2_b32 v113, v22, v23 offset1:1
	ds_write2_b32 v114, v24, v25 offset1:1
	s_waitcnt vmcnt(9)
; #define LAS __attribute__((address_space(3)))
; __device__ __forceinline__ unsigned pk2(float lo, float hi) { f32x2 v = {lo, hi}; bf16x2_t b = __builtin_convertvector(v, bf16x2_t); return __builtin_bit_cast(unsigned, b); }
; #define LDS_WAIT() asm volatile("s_waitcnt lgkmcnt(0)" ::: "memory")
; template <class MAP>
; __device__ __forceinline__ void transpose_item(const float* W, int ldw, int K, bf16_t* WT, int k0, int nd0, LAS float* scr, int lane, const MAP& map) {
;     ...
;     for (int i = 0; i < 16; ++i) { LAS float* d = scr + (4 * i + kr) * 65 + nq; d[0] = v[i].x; d[1] = v[i].y; d[2] = v[i].z; d[3] = v[i].w; }
;     LDS_WAIT(); asm volatile("" ::: "memory");
;     const int c = lane & 7;
; #pragma unroll
;     for (int j = 0; j < 8; ++j) { const int n = (lane >> 3) + 8 * j; const LAS float* s = scr + (8 * c) * 65 + n;
;         u32x4 o; o.x = pk2(s[0 * 65], s[1 * 65]); o.y = pk2(s[2 * 65], s[3 * 65]); o.z = pk2(s[4 * 65], s[5 * 65]); o.w = pk2(s[6 * 65], s[7 * 65]);
;         *(u32x4*)(WT + (size_t)(nd0 + n) * K + k0 + 8 * c) = o; }
;     LDS_WAIT(); asm volatile("" ::: "memory");
	ds_write2_b32 v115, v26, v27 offset1:1
	ds_write2_b32 v116, v28, v29 offset1:1
	s_waitcnt vmcnt(8)
	ds_write2_b32 v117, v30, v31 offset1:1
	ds_write2_b32 v118, v32, v33 offset1:1
	s_waitcnt vmcnt(7)
	ds_write2_b32 v119, v34, v35 offset1:1
	ds_write2_b32 v120, v36, v37 offset1:1
	s_waitcnt vmcnt(6)
	ds_write2_b32 v121, v38, v39 offset1:1
	ds_write2_b32 v122, v40, v41 offset1:1
	s_waitcnt vmcnt(5)
	ds_write2_b32 v123, v42, v43 offset1:1
	ds_write2_b32 v124, v44, v45 offset1:1
	s_waitcnt vmcnt(4)
	ds_write2_b32 v125, v46, v47 offset1:1
	ds_write2_b32 v126, v48, v49 offset1:1
	s_waitcnt vmcnt(3)
	ds_write2_b32 v72, v50, v51 offset1:1
	ds_write2_b32 v95, v52, v53 offset1:1
	v_add_u32_e32 v2, 0x34d0, v69
	v_add_u32_e32 v26, 0x400, v77
	v_lshlrev_b32_e32 v72, 1, v76
	v_lshl_add_u64 v[22:23], s[62:63], 0, v[72:73]
	s_waitcnt vmcnt(2)
	ds_write2_b32 v2, v54, v55 offset1:1
	v_add_u32_e32 v2, 0x34d8, v69
	ds_write2_b32 v2, v56, v57 offset1:1
	v_add_u32_e32 v2, 0x38e0, v69
	s_waitcnt vmcnt(1)
	ds_write2_b32 v2, v58, v59 offset1:1
	v_add_u32_e32 v2, 0x38e8, v69
	ds_write2_b32 v2, v60, v61 offset1:1
	v_add_u32_e32 v2, 0x3cf0, v69
	s_waitcnt vmcnt(0)
	ds_write2_b32 v2, v62, v63 offset1:1
	v_add_u32_e32 v2, 0x3cf8, v69
	ds_write2_b32 v2, v64, v65 offset1:1
	s_waitcnt lgkmcnt(0)
	ds_read2_b32 v[6:7], v77 offset0:65 offset1:73
	ds_read2_b32 v[8:9], v77 offset1:8
	ds_read2_b32 v[10:11], v77 offset0:130 offset1:138
	ds_read2_b32 v[12:13], v77 offset0:195 offset1:203
	ds_read2_b32 v[14:15], v26 offset0:4 offset1:12
	ds_read2_b32 v[16:17], v26 offset0:69 offset1:77
	ds_read2_b32 v[18:19], v26 offset0:134 offset1:142
	ds_read2_b32 v[20:21], v26 offset0:199 offset1:207
	s_waitcnt lgkmcnt(6)
	v_cvt_pk_bf16_f32 v2, v8, v6
	v_or_b32_e32 v6, s4, v71
	v_lshlrev_b32_e32 v72, 9, v6
	s_waitcnt lgkmcnt(4)
	v_cvt_pk_bf16_f32 v3, v10, v12
	s_waitcnt lgkmcnt(2)
	v_cvt_pk_bf16_f32 v4, v14, v16
	s_waitcnt lgkmcnt(0)
	v_cvt_pk_bf16_f32 v5, v18, v20
	v_lshl_add_u64 v[24:25], v[22:23], 0, v[72:73]
	global_store_dwordx4 v[24:25], v[2:5], off nt
	v_or_b32_e32 v6, s4, v98
	v_lshlrev_b32_e32 v72, 9, v6
	v_cvt_pk_bf16_f32 v2, v9, v7
	v_cvt_pk_bf16_f32 v3, v11, v13
	v_cvt_pk_bf16_f32 v4, v15, v17
	v_cvt_pk_bf16_f32 v5, v19, v21
	ds_read2_b32 v[8:9], v77 offset0:81 offset1:89
	ds_read2_b32 v[10:11], v77 offset0:16 offset1:24
	ds_read2_b32 v[12:13], v77 offset0:146 offset1:154
	ds_read2_b32 v[14:15], v77 offset0:211 offset1:219
	ds_read2_b32 v[16:17], v26 offset0:20 offset1:28
	ds_read2_b32 v[18:19], v26 offset0:85 offset1:93
	ds_read2_b32 v[20:21], v26 offset0:150 offset1:158
	ds_read2_b32 v[24:25], v26 offset0:215 offset1:223
	v_lshl_add_u64 v[6:7], v[22:23], 0, v[72:73]
	global_store_dwordx4 v[6:7], v[2:5], off nt
	v_or_b32_e32 v6, s4, v99
	v_lshlrev_b32_e32 v72, 9, v6
	s_waitcnt lgkmcnt(6)
	v_cvt_pk_bf16_f32 v2, v10, v8
	s_waitcnt lgkmcnt(4)
	v_cvt_pk_bf16_f32 v3, v12, v14
	s_waitcnt lgkmcnt(2)
	v_cvt_pk_bf16_f32 v4, v16, v18
	s_waitcnt lgkmcnt(0)
	v_cvt_pk_bf16_f32 v5, v20, v24
	v_lshl_add_u64 v[6:7], v[22:23], 0, v[72:73]
	global_store_dwordx4 v[6:7], v[2:5], off nt
	v_or_b32_e32 v6, s4, v100
	v_lshlrev_b32_e32 v72, 9, v6
	v_cvt_pk_bf16_f32 v2, v11, v9
	v_cvt_pk_bf16_f32 v3, v13, v15
	v_cvt_pk_bf16_f32 v4, v17, v19
	v_cvt_pk_bf16_f32 v5, v21, v25
	ds_read2_b32 v[8:9], v77 offset0:32 offset1:40
	ds_read2_b32 v[10:11], v77 offset0:97 offset1:105
	ds_read2_b32 v[12:13], v77 offset0:162 offset1:170
	ds_read2_b32 v[14:15], v77 offset0:227 offset1:235
	ds_read2_b32 v[16:17], v26 offset0:36 offset1:44
	ds_read2_b32 v[18:19], v26 offset0:101 offset1:109
	ds_read2_b32 v[20:21], v26 offset0:166 offset1:174
	ds_read2_b32 v[24:25], v26 offset0:231 offset1:239
	v_lshl_add_u64 v[6:7], v[22:23], 0, v[72:73]
	global_store_dwordx4 v[6:7], v[2:5], off nt
	v_or_b32_e32 v6, s4, v101
	v_lshlrev_b32_e32 v72, 9, v6
	s_waitcnt lgkmcnt(6)
	v_cvt_pk_bf16_f32 v2, v8, v10
	s_waitcnt lgkmcnt(4)
	v_cvt_pk_bf16_f32 v3, v12, v14
	s_waitcnt lgkmcnt(2)
	v_cvt_pk_bf16_f32 v4, v16, v18
	s_waitcnt lgkmcnt(0)
	v_cvt_pk_bf16_f32 v5, v20, v24
	v_lshl_add_u64 v[6:7], v[22:23], 0, v[72:73]
	global_store_dwordx4 v[6:7], v[2:5], off nt
	v_or_b32_e32 v6, s4, v102
	v_lshlrev_b32_e32 v72, 9, v6
	v_cvt_pk_bf16_f32 v2, v9, v11
	v_cvt_pk_bf16_f32 v3, v13, v15
	v_cvt_pk_bf16_f32 v4, v17, v19
	v_cvt_pk_bf16_f32 v5, v21, v25
	ds_read2_b32 v[8:9], v77 offset0:48 offset1:56
	ds_read2_b32 v[10:11], v77 offset0:113 offset1:121
	ds_read2_b32 v[12:13], v77 offset0:178 offset1:186
	ds_read2_b32 v[14:15], v77 offset0:243 offset1:251
	ds_read2_b32 v[16:17], v26 offset0:52 offset1:60
	ds_read2_b32 v[18:19], v26 offset0:117 offset1:125
	ds_read2_b32 v[20:21], v26 offset0:182 offset1:190
	ds_read2_b32 v[24:25], v26 offset0:247 offset1:255
	v_lshl_add_u64 v[6:7], v[22:23], 0, v[72:73]
	global_store_dwordx4 v[6:7], v[2:5], off nt
	v_or_b32_e32 v6, s4, v103
	v_lshlrev_b32_e32 v72, 9, v6
	s_waitcnt lgkmcnt(6)
	v_cvt_pk_bf16_f32 v2, v8, v10
	s_waitcnt lgkmcnt(4)
	v_cvt_pk_bf16_f32 v3, v12, v14
	s_waitcnt lgkmcnt(2)
	v_cvt_pk_bf16_f32 v4, v16, v18
	s_waitcnt lgkmcnt(0)
	v_cvt_pk_bf16_f32 v5, v20, v24
	v_lshl_add_u64 v[6:7], v[22:23], 0, v[72:73]
	global_store_dwordx4 v[6:7], v[2:5], off nt
	v_or_b32_e32 v6, s4, v104
	v_lshlrev_b32_e32 v72, 9, v6
	v_cvt_pk_bf16_f32 v2, v9, v11
	v_cvt_pk_bf16_f32 v3, v13, v15
	v_cvt_pk_bf16_f32 v4, v17, v19
	v_cvt_pk_bf16_f32 v5, v21, v25
	v_lshl_add_u64 v[6:7], v[22:23], 0, v[72:73]
	global_store_dwordx4 v[6:7], v[2:5], off nt
	s_waitcnt lgkmcnt(0)

; #define LAS __attribute__((address_space(3)))
; #define FIN(i) ((const float*)(const GAS float*)(((const float* const __attribute__((address_space(4)))*)__builtin_amdgcn_kernarg_segment_ptr())[i]))
; template <class MAP>
; __device__ __forceinline__ void transpose_item(const float* W, int ldw, int K, bf16_t* WT, int k0, int nd0, LAS float* scr, int lane, const MAP& map) {
;     const int nq = 4 * (lane & 15), ns = map(nd0 + nq), kr = lane >> 4;
;     f32x4 v[16];
; #pragma unroll
;     for (int i = 0; i < 16; ++i) v[i] = ns >= 0 ? *(const f32x4*)(W + (size_t)(k0 + 4 * i + kr) * ldw + ns) : (f32x4){0.f, 0.f, 0.f, 0.f};
; #pragma unroll
;     for (int i = 0; i < 16; ++i) { LAS float* d = scr + (4 * i + kr) * 65 + nq; d[0] = v[i].x; d[1] = v[i].y; d[2] = v[i].z; d[3] = v[i].w; }
; __device__ __forceinline__ void phase_prologue(Frame& F) {
;     ...
;         if (r < I_OUT) { const int kb = r / 32, nb = r % 32;
;             transpose_item(FIN(IN_WOUT) + (size_t)l * 2048 * 2048, 2048, 2048, (bf16_t*)(F.ws + WS_WOUT + l * al1m(SZ_WOUT)), 64 * kb, 64 * nb, scr, lane, MapId()); continue; } r -= I_OUT;
.LBB0_21:
	s_andn2_b64 vcc, exec, s[4:5]
	s_cbranch_vccnz .LBB0_23
	s_load_dwordx2 s[4:5], s[0:1], 0xd0
	s_ashr_i32 s9, s8, 31
	s_lshl_b64 s[62:63], s[8:9], 24
	s_mul_i32 s6, s8, 0xffffb180
	v_mov_b32_e32 v63, v73
	s_waitcnt lgkmcnt(0)
	s_add_u32 s62, s4, s62
	s_addc_u32 s63, s5, s63
	s_lshl_b64 s[4:5], s[8:9], 23
	s_add_u32 s9, s17, s4
	s_addc_u32 s5, s18, s5
	s_add_i32 s4, s29, s6
	s_and_b32 s4, s4, 0x7fc0
	s_add_i32 s6, s4, 0xffffbb00
	s_and_b32 s4, s25, 0x7c0
	v_or_b32_e32 v2, s4, v70
	v_or_b32_e32 v62, s6, v67
	v_lshlrev_b32_e32 v72, 2, v2
	v_lshl_add_u64 v[64:65], s[62:63], 0, v[72:73]
	v_or_b32_e32 v72, 4, v62
	v_lshlrev_b64 v[4:5], 13, v[72:73]
	v_or_b32_e32 v72, 8, v62
	v_lshlrev_b64 v[10:11], 13, v[72:73]
	v_or_b32_e32 v72, 12, v62
	v_lshlrev_b64 v[12:13], 13, v[72:73]
	v_or_b32_e32 v72, 16, v62
	v_lshlrev_b64 v[18:19], 13, v[72:73]
	v_or_b32_e32 v72, 20, v62
	v_lshlrev_b64 v[20:21], 13, v[72:73]
	v_or_b32_e32 v72, 24, v62
	v_lshlrev_b64 v[26:27], 13, v[72:73]
	v_or_b32_e32 v72, 28, v62
	v_lshlrev_b64 v[28:29], 13, v[72:73]
	v_or_b32_e32 v72, 32, v62
	v_lshlrev_b64 v[34:35], 13, v[72:73]
	v_or_b32_e32 v72, 36, v62
	v_lshlrev_b64 v[36:37], 13, v[72:73]
	v_or_b32_e32 v72, 40, v62
	v_lshlrev_b64 v[42:43], 13, v[72:73]
	v_or_b32_e32 v72, 44, v62
	v_lshlrev_b64 v[2:3], 13, v[62:63]
	v_lshlrev_b64 v[44:45], 13, v[72:73]
	v_or_b32_e32 v72, 48, v62
	v_lshl_add_u64 v[2:3], v[64:65], 0, v[2:3]
	v_lshl_add_u64 v[6:7], v[64:65], 0, v[4:5]
	v_lshl_add_u64 v[10:11], v[64:65], 0, v[10:11]
	v_lshl_add_u64 v[14:15], v[64:65], 0, v[12:13]
	v_lshl_add_u64 v[18:19], v[64:65], 0, v[18:19]
	v_lshl_add_u64 v[22:23], v[64:65], 0, v[20:21]
	v_lshl_add_u64 v[26:27], v[64:65], 0, v[26:27]
	v_lshl_add_u64 v[30:31], v[64:65], 0, v[28:29]
	v_lshl_add_u64 v[34:35], v[64:65], 0, v[34:35]
	v_lshl_add_u64 v[38:39], v[64:65], 0, v[36:37]
	v_lshl_add_u64 v[42:43], v[64:65], 0, v[42:43]
	v_lshl_add_u64 v[46:47], v[64:65], 0, v[44:45]
	v_lshlrev_b64 v[50:51], 13, v[72:73]
	v_or_b32_e32 v72, 52, v62
	global_load_dwordx4 v[2:5], v[2:3], off nt
	s_nop 0
	global_load_dwordx4 v[6:9], v[6:7], off nt
	s_nop 0
	global_load_dwordx4 v[10:13], v[10:11], off nt
	s_nop 0
	global_load_dwordx4 v[14:17], v[14:15], off nt
	s_nop 0
	global_load_dwordx4 v[18:21], v[18:19], off nt
	s_nop 0
	global_load_dwordx4 v[22:25], v[22:23], off nt
	s_nop 0
	global_load_dwordx4 v[26:29], v[26:27], off nt
	s_nop 0
	global_load_dwordx4 v[30:33], v[30:31], off nt
	s_nop 0
	global_load_dwordx4 v[34:37], v[34:35], off nt
	s_nop 0
	global_load_dwordx4 v[38:41], v[38:39], off nt
	s_nop 0
	global_load_dwordx4 v[42:45], v[42:43], off nt
	s_nop 0
	global_load_dwordx4 v[46:49], v[46:47], off nt
	v_lshl_add_u64 v[50:51], v[64:65], 0, v[50:51]
	v_lshlrev_b64 v[54:55], 13, v[72:73]
	global_load_dwordx4 v[50:53], v[50:51], off nt
	v_lshl_add_u64 v[54:55], v[64:65], 0, v[54:55]
	v_or_b32_e32 v72, 56, v62
	global_load_dwordx4 v[54:57], v[54:55], off nt
	v_lshlrev_b64 v[58:59], 13, v[72:73]
	v_lshl_add_u64 v[58:59], v[64:65], 0, v[58:59]
	v_or_b32_e32 v72, 60, v62
	global_load_dwordx4 v[58:61], v[58:59], off nt
	v_lshlrev_b64 v[62:63], 13, v[72:73]
	v_lshl_add_u64 v[62:63], v[64:65], 0, v[62:63]
	global_load_dwordx4 v[62:65], v[62:63], off nt
	v_add_u32_e32 v72, 0x30c0, v69
	s_lshl_b64 s[62:63], s[6:7], 1
	s_add_u32 s62, s9, s62
	s_addc_u32 s63, s5, s63
	s_waitcnt vmcnt(15)
	ds_write2_b32 v69, v2, v3 offset1:1
	ds_write2_b32 v69, v4, v5 offset0:2 offset1:3
	s_waitcnt vmcnt(14)
	ds_write2_b32 v105, v6, v7 offset1:1
	ds_write2_b32 v106, v8, v9 offset1:1
	s_waitcnt vmcnt(13)
	ds_write2_b32 v107, v10, v11 offset1:1
	ds_write2_b32 v108, v12, v13 offset1:1
	s_waitcnt vmcnt(12)
	ds_write2_b32 v109, v14, v15 offset1:1
	ds_write2_b32 v110, v16, v17 offset1:1
	s_waitcnt vmcnt(11)
	ds_write2_b32 v111, v18, v19 offset1:1
	ds_write2_b32 v112, v20, v21 offset1:1
	s_waitcnt vmcnt(10)
	ds_write2_b32 v113, v22, v23 offset1:1
	ds_write2_b32 v114, v24, v25 offset1:1
	s_waitcnt vmcnt(9)
	ds_write2_b32 v115, v26, v27 offset1:1
	ds_write2_b32 v116, v28, v29 offset1:1
	s_waitcnt vmcnt(8)
	ds_write2_b32 v117, v30, v31 offset1:1
	ds_write2_b32 v118, v32, v33 offset1:1
	s_waitcnt vmcnt(7)
	ds_write2_b32 v119, v34, v35 offset1:1
	ds_write2_b32 v120, v36, v37 offset1:1
	s_waitcnt vmcnt(6)
	ds_write2_b32 v121, v38, v39 offset1:1
	ds_write2_b32 v122, v40, v41 offset1:1
	s_waitcnt vmcnt(5)
	ds_write2_b32 v123, v42, v43 offset1:1
	ds_write2_b32 v124, v44, v45 offset1:1
	s_waitcnt vmcnt(4)
	ds_write2_b32 v125, v46, v47 offset1:1
	ds_write2_b32 v126, v48, v49 offset1:1
	s_waitcnt vmcnt(3)
	ds_write2_b32 v72, v50, v51 offset1:1
	v_add_u32_e32 v2, 0x30c8, v69
	v_add_u32_e32 v26, 0x400, v77
	ds_write2_b32 v2, v52, v53 offset1:1
	v_add_u32_e32 v2, 0x34d0, v69
	v_lshlrev_b32_e32 v72, 1, v76
	s_waitcnt vmcnt(2)
; #define LAS __attribute__((address_space(3)))
; __device__ __forceinline__ unsigned pk2(float lo, float hi) { f32x2 v = {lo, hi}; bf16x2_t b = __builtin_convertvector(v, bf16x2_t); return __builtin_bit_cast(unsigned, b); }
; #define LDS_WAIT() asm volatile("s_waitcnt lgkmcnt(0)" ::: "memory")
; template <class MAP>
; __device__ __forceinline__ void transpose_item(const float* W, int ldw, int K, bf16_t* WT, int k0, int nd0, LAS float* scr, int lane, const MAP& map) {
;     ...
;     for (int i = 0; i < 16; ++i) { LAS float* d = scr + (4 * i + kr) * 65 + nq; d[0] = v[i].x; d[1] = v[i].y; d[2] = v[i].z; d[3] = v[i].w; }
;     LDS_WAIT(); asm volatile("" ::: "memory");
;     const int c = lane & 7;
; #pragma unroll
;     for (int j = 0; j < 8; ++j) { const int n = (lane >> 3) + 8 * j; const LAS float* s = scr + (8 * c) * 65 + n;
;         u32x4 o; o.x = pk2(s[0 * 65], s[1 * 65]); o.y = pk2(s[2 * 65], s[3 * 65]); o.z = pk2(s[4 * 65], s[5 * 65]); o.w = pk2(s[6 * 65], s[7 * 65]);
;         *(u32x4*)(WT + (size_t)(nd0 + n) * K + k0 + 8 * c) = o; }
;     LDS_WAIT(); asm volatile("" ::: "memory");
	ds_write2_b32 v2, v54, v55 offset1:1
	v_add_u32_e32 v2, 0x34d8, v69
	ds_write2_b32 v2, v56, v57 offset1:1
	v_add_u32_e32 v2, 0x38e0, v69
	s_waitcnt vmcnt(1)
	ds_write2_b32 v2, v58, v59 offset1:1
	v_add_u32_e32 v2, 0x38e8, v69
	ds_write2_b32 v2, v60, v61 offset1:1
	v_add_u32_e32 v2, 0x3cf0, v69
	s_waitcnt vmcnt(0)
	ds_write2_b32 v2, v62, v63 offset1:1
	v_add_u32_e32 v2, 0x3cf8, v69
	ds_write2_b32 v2, v64, v65 offset1:1
	s_waitcnt lgkmcnt(0)
	ds_read2_b32 v[6:7], v77 offset0:65 offset1:73
	ds_read2_b32 v[8:9], v77 offset1:8
	ds_read2_b32 v[10:11], v77 offset0:130 offset1:138
	ds_read2_b32 v[12:13], v77 offset0:195 offset1:203
	ds_read2_b32 v[14:15], v26 offset0:4 offset1:12
	ds_read2_b32 v[16:17], v26 offset0:69 offset1:77
	ds_read2_b32 v[18:19], v26 offset0:134 offset1:142
	ds_read2_b32 v[20:21], v26 offset0:199 offset1:207
	v_lshl_add_u64 v[22:23], s[62:63], 0, v[72:73]
	s_waitcnt lgkmcnt(6)
	v_cvt_pk_bf16_f32 v2, v8, v6
	v_or_b32_e32 v6, s4, v71
	v_lshlrev_b32_e32 v72, 12, v6
	s_waitcnt lgkmcnt(4)
	v_cvt_pk_bf16_f32 v3, v10, v12
	s_waitcnt lgkmcnt(2)
	v_cvt_pk_bf16_f32 v4, v14, v16
	s_waitcnt lgkmcnt(0)
	v_cvt_pk_bf16_f32 v5, v18, v20
	v_lshl_add_u64 v[24:25], v[22:23], 0, v[72:73]
	global_store_dwordx4 v[24:25], v[2:5], off nt
	v_or_b32_e32 v6, s4, v98
	v_lshlrev_b32_e32 v72, 12, v6
	v_cvt_pk_bf16_f32 v2, v9, v7
	v_cvt_pk_bf16_f32 v3, v11, v13
	v_cvt_pk_bf16_f32 v4, v15, v17
	v_cvt_pk_bf16_f32 v5, v19, v21
	ds_read2_b32 v[8:9], v77 offset0:81 offset1:89
	ds_read2_b32 v[10:11], v77 offset0:16 offset1:24
	ds_read2_b32 v[12:13], v77 offset0:146 offset1:154
	ds_read2_b32 v[14:15], v77 offset0:211 offset1:219
	ds_read2_b32 v[16:17], v26 offset0:20 offset1:28
	ds_read2_b32 v[18:19], v26 offset0:85 offset1:93
	ds_read2_b32 v[20:21], v26 offset0:150 offset1:158
	ds_read2_b32 v[24:25], v26 offset0:215 offset1:223
	v_lshl_add_u64 v[6:7], v[22:23], 0, v[72:73]
	global_store_dwordx4 v[6:7], v[2:5], off nt
	v_or_b32_e32 v6, s4, v99
	v_lshlrev_b32_e32 v72, 12, v6
	s_waitcnt lgkmcnt(6)
	v_cvt_pk_bf16_f32 v2, v10, v8
	s_waitcnt lgkmcnt(4)
	v_cvt_pk_bf16_f32 v3, v12, v14
	s_waitcnt lgkmcnt(2)
	v_cvt_pk_bf16_f32 v4, v16, v18
	s_waitcnt lgkmcnt(0)
	v_cvt_pk_bf16_f32 v5, v20, v24
	v_lshl_add_u64 v[6:7], v[22:23], 0, v[72:73]
	global_store_dwordx4 v[6:7], v[2:5], off nt
	v_or_b32_e32 v6, s4, v100
	v_lshlrev_b32_e32 v72, 12, v6
	v_cvt_pk_bf16_f32 v2, v11, v9
	v_cvt_pk_bf16_f32 v3, v13, v15
	v_cvt_pk_bf16_f32 v4, v17, v19
	v_cvt_pk_bf16_f32 v5, v21, v25
	ds_read2_b32 v[8:9], v77 offset0:32 offset1:40
	ds_read2_b32 v[10:11], v77 offset0:97 offset1:105
	ds_read2_b32 v[12:13], v77 offset0:162 offset1:170
	ds_read2_b32 v[14:15], v77 offset0:227 offset1:235
	ds_read2_b32 v[16:17], v26 offset0:36 offset1:44
	ds_read2_b32 v[18:19], v26 offset0:101 offset1:109
	ds_read2_b32 v[20:21], v26 offset0:166 offset1:174
	ds_read2_b32 v[24:25], v26 offset0:231 offset1:239
	v_lshl_add_u64 v[6:7], v[22:23], 0, v[72:73]
	global_store_dwordx4 v[6:7], v[2:5], off nt
	v_or_b32_e32 v6, s4, v101
	v_lshlrev_b32_e32 v72, 12, v6
	s_waitcnt lgkmcnt(6)
	v_cvt_pk_bf16_f32 v2, v8, v10
	s_waitcnt lgkmcnt(4)
	v_cvt_pk_bf16_f32 v3, v12, v14
	s_waitcnt lgkmcnt(2)
	v_cvt_pk_bf16_f32 v4, v16, v18
	s_waitcnt lgkmcnt(0)
	v_cvt_pk_bf16_f32 v5, v20, v24
	v_lshl_add_u64 v[6:7], v[22:23], 0, v[72:73]
	global_store_dwordx4 v[6:7], v[2:5], off nt
	v_or_b32_e32 v6, s4, v102
	v_lshlrev_b32_e32 v72, 12, v6
	v_cvt_pk_bf16_f32 v2, v9, v11
	v_cvt_pk_bf16_f32 v3, v13, v15
	v_cvt_pk_bf16_f32 v4, v17, v19
	v_cvt_pk_bf16_f32 v5, v21, v25
	ds_read2_b32 v[8:9], v77 offset0:48 offset1:56
	ds_read2_b32 v[10:11], v77 offset0:113 offset1:121
	ds_read2_b32 v[12:13], v77 offset0:178 offset1:186
	ds_read2_b32 v[14:15], v77 offset0:243 offset1:251
	ds_read2_b32 v[16:17], v26 offset0:52 offset1:60
	ds_read2_b32 v[18:19], v26 offset0:117 offset1:125
	ds_read2_b32 v[20:21], v26 offset0:182 offset1:190
	ds_read2_b32 v[24:25], v26 offset0:247 offset1:255
	v_lshl_add_u64 v[6:7], v[22:23], 0, v[72:73]
	global_store_dwordx4 v[6:7], v[2:5], off nt
	v_or_b32_e32 v6, s4, v103
	v_lshlrev_b32_e32 v72, 12, v6
	s_waitcnt lgkmcnt(6)
	v_cvt_pk_bf16_f32 v2, v8, v10
	s_waitcnt lgkmcnt(4)
	v_cvt_pk_bf16_f32 v3, v12, v14
	s_waitcnt lgkmcnt(2)
	v_cvt_pk_bf16_f32 v4, v16, v18
	s_waitcnt lgkmcnt(0)
	v_cvt_pk_bf16_f32 v5, v20, v24
	v_lshl_add_u64 v[6:7], v[22:23], 0, v[72:73]
	global_store_dwordx4 v[6:7], v[2:5], off nt
	v_or_b32_e32 v6, s4, v104
	v_lshlrev_b32_e32 v72, 12, v6
	v_cvt_pk_bf16_f32 v2, v9, v11
	v_cvt_pk_bf16_f32 v3, v13, v15
	v_cvt_pk_bf16_f32 v4, v17, v19
	v_cvt_pk_bf16_f32 v5, v21, v25
	v_lshl_add_u64 v[6:7], v[22:23], 0, v[72:73]
	global_store_dwordx4 v[6:7], v[2:5], off nt
	s_waitcnt lgkmcnt(0)

; #define LAS __attribute__((address_space(3)))
; #define FIN(i) ((const float*)(const GAS float*)(((const float* const __attribute__((address_space(4)))*)__builtin_amdgcn_kernarg_segment_ptr())[i]))
; template <class MAP>
; __device__ __forceinline__ void transpose_item(const float* W, int ldw, int K, bf16_t* WT, int k0, int nd0, LAS float* scr, int lane, const MAP& map) {
;     const int nq = 4 * (lane & 15), ns = map(nd0 + nq), kr = lane >> 4;
;     f32x4 v[16];
; #pragma unroll
;     for (int i = 0; i < 16; ++i) v[i] = ns >= 0 ? *(const f32x4*)(W + (size_t)(k0 + 4 * i + kr) * ldw + ns) : (f32x4){0.f, 0.f, 0.f, 0.f};
; #pragma unroll
;     for (int i = 0; i < 16; ++i) { LAS float* d = scr + (4 * i + kr) * 65 + nq; d[0] = v[i].x; d[1] = v[i].y; d[2] = v[i].z; d[3] = v[i].w; }
; __device__ __forceinline__ void phase_prologue(Frame& F) {
;     ...
;         if (r < 3 * I_BR) { const int z = r / I_BR, rr = r % I_BR, kb = rr / 32, nb = rr % 32;
;             const float* src = FIN(IN_WBRP + z) + (size_t)l * 1024 * 2048;
;             transpose_item(src, 2048, 1024, (bf16_t*)(F.ws + WS_WBR + l * al1m(SZ_WBR)) + (size_t)z * 2048 * 1024, 64 * kb, 64 * nb, scr, lane, MapId()); continue; } r -= 3 * I_BR;
.LBB0_24:
	s_andn2_b64 vcc, exec, s[4:5]
	s_cbranch_vccnz .LBB0_26
	s_add_i32 s4, s10, 0xffffe380
	s_lshr_b32 s6, s4, 9
	s_lshl_b32 s4, s6, 3
	s_load_dwordx2 s[4:5], s[0:1], s4 offset:0xb8
	s_ashr_i32 s9, s8, 31
	s_lshl_b64 s[62:63], s[8:9], 23
	s_mul_i32 s64, s8, 0xc00000
	s_mul_hi_i32 s11, s8, 0xc00000
	s_waitcnt lgkmcnt(0)
	s_add_u32 s62, s4, s62
	s_addc_u32 s63, s5, s63
	s_add_u32 s9, s19, s64
	s_addc_u32 s11, s20, s11
	s_lshl_b64 s[4:5], s[6:7], 22
	s_add_u32 s6, s9, s4
	s_mul_i32 s4, s8, 0xffffb180
	s_addc_u32 s5, s11, s5
	s_add_i32 s4, s29, s4
	s_addk_i32 s4, 0xc700
	s_and_b32 s9, s4, 0x3c0
	s_and_b32 s4, s25, 0x7c0
	v_or_b32_e32 v2, s4, v70
	v_or_b32_e32 v4, s9, v67
	v_lshlrev_b32_e32 v72, 2, v2
	v_lshl_add_u64 v[2:3], s[62:63], 0, v[72:73]
	v_lshlrev_b32_e32 v72, 13, v4
	v_lshl_add_u64 v[62:63], v[2:3], 0, v[72:73]
	v_add_co_u32_e32 v6, vcc, s39, v62
	s_lshl_b32 s9, s9, 1
	s_nop 0
	v_addc_co_u32_e32 v7, vcc, 0, v63, vcc
	v_add_co_u32_e32 v10, vcc, s44, v62
	global_load_dwordx4 v[2:5], v[62:63], off nt
	s_nop 0
	global_load_dwordx4 v[6:9], v[6:7], off nt
	v_addc_co_u32_e32 v11, vcc, 0, v63, vcc
	v_add_co_u32_e32 v14, vcc, s45, v62
	s_add_u32 s62, s6, s9
	s_nop 0
	v_addc_co_u32_e32 v15, vcc, 0, v63, vcc
	v_add_co_u32_e32 v18, vcc, s46, v62
	global_load_dwordx4 v[10:13], v[10:11], off nt
	s_nop 0
	global_load_dwordx4 v[14:17], v[14:15], off nt
	v_addc_co_u32_e32 v19, vcc, 0, v63, vcc
	v_add_co_u32_e32 v22, vcc, s47, v62
	s_addc_u32 s63, s5, 0
	s_nop 0
	v_addc_co_u32_e32 v23, vcc, 0, v63, vcc
	v_add_co_u32_e32 v26, vcc, s48, v62
	global_load_dwordx4 v[18:21], v[18:19], off nt
	s_nop 0
	global_load_dwordx4 v[22:25], v[22:23], off nt
	v_addc_co_u32_e32 v27, vcc, 0, v63, vcc
	v_add_co_u32_e32 v30, vcc, s49, v62
	v_lshlrev_b32_e32 v72, 1, v76
	s_nop 0
	v_addc_co_u32_e32 v31, vcc, 0, v63, vcc
	v_add_co_u32_e32 v34, vcc, s50, v62
	global_load_dwordx4 v[26:29], v[26:27], off nt
	s_nop 0
	global_load_dwordx4 v[30:33], v[30:31], off nt
	v_addc_co_u32_e32 v35, vcc, 0, v63, vcc
	v_add_co_u32_e32 v38, vcc, s51, v62
	s_nop 1
	v_addc_co_u32_e32 v39, vcc, 0, v63, vcc
	v_add_co_u32_e32 v42, vcc, s52, v62
	global_load_dwordx4 v[34:37], v[34:35], off nt
	s_nop 0
	global_load_dwordx4 v[38:41], v[38:39], off nt
	v_addc_co_u32_e32 v43, vcc, 0, v63, vcc
	v_add_co_u32_e32 v46, vcc, s53, v62
	s_nop 1
	v_addc_co_u32_e32 v47, vcc, 0, v63, vcc
	v_add_co_u32_e32 v50, vcc, s54, v62
	global_load_dwordx4 v[42:45], v[42:43], off nt
	s_nop 0
	global_load_dwordx4 v[46:49], v[46:47], off nt
	v_addc_co_u32_e32 v51, vcc, 0, v63, vcc
	global_load_dwordx4 v[50:53], v[50:51], off nt
	v_add_co_u32_e32 v54, vcc, s55, v62
	s_nop 1
	v_addc_co_u32_e32 v55, vcc, 0, v63, vcc
	global_load_dwordx4 v[54:57], v[54:55], off nt
	v_add_co_u32_e32 v58, vcc, s56, v62
	s_nop 1
	v_addc_co_u32_e32 v59, vcc, 0, v63, vcc
	global_load_dwordx4 v[58:61], v[58:59], off nt
	v_add_co_u32_e32 v62, vcc, s57, v62
	s_nop 1
	v_addc_co_u32_e32 v63, vcc, 0, v63, vcc
	global_load_dwordx4 v[62:65], v[62:63], off nt
	s_waitcnt vmcnt(15)
	ds_write2_b32 v69, v2, v3 offset1:1
	ds_write2_b32 v69, v4, v5 offset0:2 offset1:3
	s_waitcnt vmcnt(14)
	ds_write2_b32 v105, v6, v7 offset1:1
	ds_write2_b32 v106, v8, v9 offset1:1
	s_waitcnt vmcnt(13)
	ds_write2_b32 v107, v10, v11 offset1:1
	ds_write2_b32 v108, v12, v13 offset1:1
	s_waitcnt vmcnt(12)
	ds_write2_b32 v109, v14, v15 offset1:1
	ds_write2_b32 v110, v16, v17 offset1:1
	s_waitcnt vmcnt(11)
	ds_write2_b32 v111, v18, v19 offset1:1
	ds_write2_b32 v112, v20, v21 offset1:1
	s_waitcnt vmcnt(10)
	ds_write2_b32 v113, v22, v23 offset1:1
	ds_write2_b32 v114, v24, v25 offset1:1
	s_waitcnt vmcnt(9)
	ds_write2_b32 v115, v26, v27 offset1:1
	ds_write2_b32 v116, v28, v29 offset1:1
	s_waitcnt vmcnt(8)
	ds_write2_b32 v117, v30, v31 offset1:1
	ds_write2_b32 v118, v32, v33 offset1:1
	s_waitcnt vmcnt(7)
	ds_write2_b32 v119, v34, v35 offset1:1
	ds_write2_b32 v120, v36, v37 offset1:1
	s_waitcnt vmcnt(6)
	ds_write2_b32 v121, v38, v39 offset1:1
	ds_write2_b32 v122, v40, v41 offset1:1
	s_waitcnt vmcnt(5)
	ds_write2_b32 v123, v42, v43 offset1:1
	ds_write2_b32 v124, v44, v45 offset1:1
	s_waitcnt vmcnt(4)
	ds_write2_b32 v125, v46, v47 offset1:1
	ds_write2_b32 v126, v48, v49 offset1:1
	v_add_u32_e32 v2, 0x30c0, v69
	v_add_u32_e32 v26, 0x400, v77
	s_waitcnt vmcnt(3)
	ds_write2_b32 v2, v50, v51 offset1:1
	v_add_u32_e32 v2, 0x30c8, v69
	ds_write2_b32 v2, v52, v53 offset1:1
	v_add_u32_e32 v2, 0x34d0, v69
	v_lshl_add_u64 v[22:23], s[62:63], 0, v[72:73]
	s_waitcnt vmcnt(2)
; #define LAS __attribute__((address_space(3)))
; __device__ __forceinline__ unsigned pk2(float lo, float hi) { f32x2 v = {lo, hi}; bf16x2_t b = __builtin_convertvector(v, bf16x2_t); return __builtin_bit_cast(unsigned, b); }
; #define LDS_WAIT() asm volatile("s_waitcnt lgkmcnt(0)" ::: "memory")
; template <class MAP>
; __device__ __forceinline__ void transpose_item(const float* W, int ldw, int K, bf16_t* WT, int k0, int nd0, LAS float* scr, int lane, const MAP& map) {
;     ...
;     for (int i = 0; i < 16; ++i) { LAS float* d = scr + (4 * i + kr) * 65 + nq; d[0] = v[i].x; d[1] = v[i].y; d[2] = v[i].z; d[3] = v[i].w; }
;     LDS_WAIT(); asm volatile("" ::: "memory");
;     const int c = lane & 7;
; #pragma unroll
;     for (int j = 0; j < 8; ++j) { const int n = (lane >> 3) + 8 * j; const LAS float* s = scr + (8 * c) * 65 + n;
;         u32x4 o; o.x = pk2(s[0 * 65], s[1 * 65]); o.y = pk2(s[2 * 65], s[3 * 65]); o.z = pk2(s[4 * 65], s[5 * 65]); o.w = pk2(s[6 * 65], s[7 * 65]);
;         *(u32x4*)(WT + (size_t)(nd0 + n) * K + k0 + 8 * c) = o; }
;     LDS_WAIT(); asm volatile("" ::: "memory");
	ds_write2_b32 v2, v54, v55 offset1:1
	v_add_u32_e32 v2, 0x34d8, v69
	ds_write2_b32 v2, v56, v57 offset1:1
	v_add_u32_e32 v2, 0x38e0, v69
	s_waitcnt vmcnt(1)
	ds_write2_b32 v2, v58, v59 offset1:1
	v_add_u32_e32 v2, 0x38e8, v69
	ds_write2_b32 v2, v60, v61 offset1:1
	v_add_u32_e32 v2, 0x3cf0, v69
	s_waitcnt vmcnt(0)
	ds_write2_b32 v2, v62, v63 offset1:1
	v_add_u32_e32 v2, 0x3cf8, v69
	ds_write2_b32 v2, v64, v65 offset1:1
	s_waitcnt lgkmcnt(0)
	ds_read2_b32 v[6:7], v77 offset0:65 offset1:73
	ds_read2_b32 v[8:9], v77 offset1:8
	ds_read2_b32 v[10:11], v77 offset0:130 offset1:138
	ds_read2_b32 v[12:13], v77 offset0:195 offset1:203
	ds_read2_b32 v[14:15], v26 offset0:4 offset1:12
	ds_read2_b32 v[16:17], v26 offset0:69 offset1:77
	ds_read2_b32 v[18:19], v26 offset0:134 offset1:142
	ds_read2_b32 v[20:21], v26 offset0:199 offset1:207
	s_waitcnt lgkmcnt(6)
	v_cvt_pk_bf16_f32 v2, v8, v6
	v_or_b32_e32 v6, s4, v71
	v_lshlrev_b32_e32 v72, 11, v6
	s_waitcnt lgkmcnt(4)
	v_cvt_pk_bf16_f32 v3, v10, v12
	s_waitcnt lgkmcnt(2)
	v_cvt_pk_bf16_f32 v4, v14, v16
	s_waitcnt lgkmcnt(0)
	v_cvt_pk_bf16_f32 v5, v18, v20
	v_lshl_add_u64 v[24:25], v[22:23], 0, v[72:73]
	global_store_dwordx4 v[24:25], v[2:5], off nt
	v_or_b32_e32 v6, s4, v98
	v_lshlrev_b32_e32 v72, 11, v6
	v_cvt_pk_bf16_f32 v2, v9, v7
	v_cvt_pk_bf16_f32 v3, v11, v13
	v_cvt_pk_bf16_f32 v4, v15, v17
	v_cvt_pk_bf16_f32 v5, v19, v21
	ds_read2_b32 v[8:9], v77 offset0:81 offset1:89
	ds_read2_b32 v[10:11], v77 offset0:16 offset1:24
	ds_read2_b32 v[12:13], v77 offset0:146 offset1:154
	ds_read2_b32 v[14:15], v77 offset0:211 offset1:219
	ds_read2_b32 v[16:17], v26 offset0:20 offset1:28
	ds_read2_b32 v[18:19], v26 offset0:85 offset1:93
	ds_read2_b32 v[20:21], v26 offset0:150 offset1:158
	ds_read2_b32 v[24:25], v26 offset0:215 offset1:223
	v_lshl_add_u64 v[6:7], v[22:23], 0, v[72:73]
	global_store_dwordx4 v[6:7], v[2:5], off nt
	v_or_b32_e32 v6, s4, v99
	v_lshlrev_b32_e32 v72, 11, v6
	s_waitcnt lgkmcnt(6)
	v_cvt_pk_bf16_f32 v2, v10, v8
	s_waitcnt lgkmcnt(4)
	v_cvt_pk_bf16_f32 v3, v12, v14
	s_waitcnt lgkmcnt(2)
	v_cvt_pk_bf16_f32 v4, v16, v18
	s_waitcnt lgkmcnt(0)
	v_cvt_pk_bf16_f32 v5, v20, v24
	v_lshl_add_u64 v[6:7], v[22:23], 0, v[72:73]
	global_store_dwordx4 v[6:7], v[2:5], off nt
	v_or_b32_e32 v6, s4, v100
	v_lshlrev_b32_e32 v72, 11, v6
	v_cvt_pk_bf16_f32 v2, v11, v9
	v_cvt_pk_bf16_f32 v3, v13, v15
	v_cvt_pk_bf16_f32 v4, v17, v19
	v_cvt_pk_bf16_f32 v5, v21, v25
	ds_read2_b32 v[8:9], v77 offset0:32 offset1:40
	ds_read2_b32 v[10:11], v77 offset0:97 offset1:105
	ds_read2_b32 v[12:13], v77 offset0:162 offset1:170
	ds_read2_b32 v[14:15], v77 offset0:227 offset1:235
	ds_read2_b32 v[16:17], v26 offset0:36 offset1:44
	ds_read2_b32 v[18:19], v26 offset0:101 offset1:109
	ds_read2_b32 v[20:21], v26 offset0:166 offset1:174
	ds_read2_b32 v[24:25], v26 offset0:231 offset1:239
	v_lshl_add_u64 v[6:7], v[22:23], 0, v[72:73]
	global_store_dwordx4 v[6:7], v[2:5], off nt
	v_or_b32_e32 v6, s4, v101
	v_lshlrev_b32_e32 v72, 11, v6
	s_waitcnt lgkmcnt(6)
	v_cvt_pk_bf16_f32 v2, v8, v10
	s_waitcnt lgkmcnt(4)
	v_cvt_pk_bf16_f32 v3, v12, v14
	s_waitcnt lgkmcnt(2)
	v_cvt_pk_bf16_f32 v4, v16, v18
	s_waitcnt lgkmcnt(0)
	v_cvt_pk_bf16_f32 v5, v20, v24
	v_lshl_add_u64 v[6:7], v[22:23], 0, v[72:73]
	global_store_dwordx4 v[6:7], v[2:5], off nt
	v_or_b32_e32 v6, s4, v102
	v_lshlrev_b32_e32 v72, 11, v6
	v_cvt_pk_bf16_f32 v2, v9, v11
	v_cvt_pk_bf16_f32 v3, v13, v15
	v_cvt_pk_bf16_f32 v4, v17, v19
	v_cvt_pk_bf16_f32 v5, v21, v25
	ds_read2_b32 v[8:9], v77 offset0:48 offset1:56
	ds_read2_b32 v[10:11], v77 offset0:113 offset1:121
	ds_read2_b32 v[12:13], v77 offset0:178 offset1:186
	ds_read2_b32 v[14:15], v77 offset0:243 offset1:251
	ds_read2_b32 v[16:17], v26 offset0:52 offset1:60
	ds_read2_b32 v[18:19], v26 offset0:117 offset1:125
	ds_read2_b32 v[20:21], v26 offset0:182 offset1:190
	ds_read2_b32 v[24:25], v26 offset0:247 offset1:255
	v_lshl_add_u64 v[6:7], v[22:23], 0, v[72:73]
	global_store_dwordx4 v[6:7], v[2:5], off nt
	v_or_b32_e32 v6, s4, v103
	v_lshlrev_b32_e32 v72, 11, v6
	s_waitcnt lgkmcnt(6)
	v_cvt_pk_bf16_f32 v2, v8, v10
	s_waitcnt lgkmcnt(4)
	v_cvt_pk_bf16_f32 v3, v12, v14
	s_waitcnt lgkmcnt(2)
	v_cvt_pk_bf16_f32 v4, v16, v18
	s_waitcnt lgkmcnt(0)
	v_cvt_pk_bf16_f32 v5, v20, v24
	v_lshl_add_u64 v[6:7], v[22:23], 0, v[72:73]
	global_store_dwordx4 v[6:7], v[2:5], off nt
	v_or_b32_e32 v6, s4, v104
	v_lshlrev_b32_e32 v72, 11, v6
	v_cvt_pk_bf16_f32 v2, v9, v11
	v_cvt_pk_bf16_f32 v3, v13, v15
	v_cvt_pk_bf16_f32 v4, v17, v19
	v_cvt_pk_bf16_f32 v5, v21, v25
	v_lshl_add_u64 v[6:7], v[22:23], 0, v[72:73]
	global_store_dwordx4 v[6:7], v[2:5], off nt
	s_waitcnt lgkmcnt(0)

; #define LAS __attribute__((address_space(3)))
; #define FIN(i) ((const float*)(const GAS float*)(((const float* const __attribute__((address_space(4)))*)__builtin_amdgcn_kernarg_segment_ptr())[i]))
; template <class MAP>
; __device__ __forceinline__ void transpose_item(const float* W, int ldw, int K, bf16_t* WT, int k0, int nd0, LAS float* scr, int lane, const MAP& map) {
;     const int nq = 4 * (lane & 15), ns = map(nd0 + nq), kr = lane >> 4;
;     f32x4 v[16];
; #pragma unroll
;     for (int i = 0; i < 16; ++i) v[i] = ns >= 0 ? *(const f32x4*)(W + (size_t)(k0 + 4 * i + kr) * ldw + ns) : (f32x4){0.f, 0.f, 0.f, 0.f};
; #pragma unroll
;     for (int i = 0; i < 16; ++i) { LAS float* d = scr + (4 * i + kr) * 65 + nq; d[0] = v[i].x; d[1] = v[i].y; d[2] = v[i].z; d[3] = v[i].w; }
; __device__ __forceinline__ void phase_prologue(Frame& F) {
;     ...
;         if (r < I_GLU) { const int kb = r / 16, nb = r % 16;
;             transpose_item(FIN(IN_WGLU) + (size_t)l * 1024 * 1024, 1024, 1024, (bf16_t*)(F.ws + WS_WGLU + l * al1m(SZ_WGLU)), 64 * kb, 64 * nb, scr, lane, MapId()); continue; } r -= I_GLU;
.LBB0_27:
	s_andn2_b64 vcc, exec, s[4:5]
	s_cbranch_vccnz .LBB0_29
	s_load_dwordx2 s[4:5], s[0:1], 0xb0
	s_ashr_i32 s9, s8, 31
	s_lshl_b64 s[62:63], s[8:9], 22
	s_mul_i32 s6, s8, 0xffff6300
	v_mov_b32_e32 v63, v73
	s_waitcnt lgkmcnt(0)
	s_add_u32 s62, s4, s62
	s_addc_u32 s63, s5, s63
	s_lshl_b64 s[4:5], s[8:9], 21
	s_add_u32 s9, s21, s4
	s_addc_u32 s5, s22, s5
	s_add_i32 s4, s27, s6
	s_and_b32 s4, s4, 0x7fc0
	s_add_i32 s6, s4, 0xffff9200
	s_and_b32 s4, s25, 0x3c0
	v_or_b32_e32 v2, s4, v70
	v_or_b32_e32 v62, s6, v67
	v_lshlrev_b32_e32 v72, 2, v2
	v_lshl_add_u64 v[64:65], s[62:63], 0, v[72:73]
	v_or_b32_e32 v72, 4, v62
	v_lshlrev_b64 v[4:5], 12, v[72:73]
	v_or_b32_e32 v72, 8, v62
	v_lshlrev_b64 v[10:11], 12, v[72:73]
	v_or_b32_e32 v72, 12, v62
	v_lshlrev_b64 v[12:13], 12, v[72:73]
	v_or_b32_e32 v72, 16, v62
	v_lshlrev_b64 v[18:19], 12, v[72:73]
	v_or_b32_e32 v72, 20, v62
	v_lshlrev_b64 v[20:21], 12, v[72:73]
	v_or_b32_e32 v72, 24, v62
	v_lshlrev_b64 v[26:27], 12, v[72:73]
	v_or_b32_e32 v72, 28, v62
	v_lshlrev_b64 v[28:29], 12, v[72:73]
	v_or_b32_e32 v72, 32, v62
	v_lshlrev_b64 v[34:35], 12, v[72:73]
	v_or_b32_e32 v72, 36, v62
	v_lshlrev_b64 v[36:37], 12, v[72:73]
	v_or_b32_e32 v72, 40, v62
	v_lshlrev_b64 v[42:43], 12, v[72:73]
	v_or_b32_e32 v72, 44, v62
	v_lshlrev_b64 v[2:3], 12, v[62:63]
	v_lshlrev_b64 v[44:45], 12, v[72:73]
	v_or_b32_e32 v72, 48, v62
	v_lshl_add_u64 v[2:3], v[64:65], 0, v[2:3]
	v_lshl_add_u64 v[6:7], v[64:65], 0, v[4:5]
	v_lshl_add_u64 v[10:11], v[64:65], 0, v[10:11]
	v_lshl_add_u64 v[14:15], v[64:65], 0, v[12:13]
	v_lshl_add_u64 v[18:19], v[64:65], 0, v[18:19]
	v_lshl_add_u64 v[22:23], v[64:65], 0, v[20:21]
	v_lshl_add_u64 v[26:27], v[64:65], 0, v[26:27]
	v_lshl_add_u64 v[30:31], v[64:65], 0, v[28:29]
	v_lshl_add_u64 v[34:35], v[64:65], 0, v[34:35]
	v_lshl_add_u64 v[38:39], v[64:65], 0, v[36:37]
	v_lshl_add_u64 v[42:43], v[64:65], 0, v[42:43]
	v_lshl_add_u64 v[46:47], v[64:65], 0, v[44:45]
	v_lshlrev_b64 v[50:51], 12, v[72:73]
	v_or_b32_e32 v72, 52, v62
	global_load_dwordx4 v[2:5], v[2:3], off nt
	s_nop 0
	global_load_dwordx4 v[6:9], v[6:7], off nt
	s_nop 0
	global_load_dwordx4 v[10:13], v[10:11], off nt
	s_nop 0
	global_load_dwordx4 v[14:17], v[14:15], off nt
	s_nop 0
	global_load_dwordx4 v[18:21], v[18:19], off nt
	s_nop 0
	global_load_dwordx4 v[22:25], v[22:23], off nt
	s_nop 0
	global_load_dwordx4 v[26:29], v[26:27], off nt
	s_nop 0
	global_load_dwordx4 v[30:33], v[30:31], off nt
	s_nop 0
	global_load_dwordx4 v[34:37], v[34:35], off nt
	s_nop 0
	global_load_dwordx4 v[38:41], v[38:39], off nt
	s_nop 0
	global_load_dwordx4 v[42:45], v[42:43], off nt
	s_nop 0
	global_load_dwordx4 v[46:49], v[46:47], off nt
	v_lshl_add_u64 v[50:51], v[64:65], 0, v[50:51]
	v_lshlrev_b64 v[54:55], 12, v[72:73]
	global_load_dwordx4 v[50:53], v[50:51], off nt
	v_lshl_add_u64 v[54:55], v[64:65], 0, v[54:55]
	v_or_b32_e32 v72, 56, v62
	global_load_dwordx4 v[54:57], v[54:55], off nt
	v_lshlrev_b64 v[58:59], 12, v[72:73]
	v_lshl_add_u64 v[58:59], v[64:65], 0, v[58:59]
	v_or_b32_e32 v72, 60, v62
	global_load_dwordx4 v[58:61], v[58:59], off nt
	v_lshlrev_b64 v[62:63], 12, v[72:73]
	v_lshl_add_u64 v[62:63], v[64:65], 0, v[62:63]
	global_load_dwordx4 v[62:65], v[62:63], off nt
	v_add_u32_e32 v72, 0x30c0, v69
	s_lshl_b64 s[62:63], s[6:7], 1
	s_add_u32 s62, s9, s62
	s_addc_u32 s63, s5, s63
	s_waitcnt vmcnt(15)
	ds_write2_b32 v69, v2, v3 offset1:1
	ds_write2_b32 v69, v4, v5 offset0:2 offset1:3
	s_waitcnt vmcnt(14)
	ds_write2_b32 v105, v6, v7 offset1:1
	ds_write2_b32 v106, v8, v9 offset1:1
	s_waitcnt vmcnt(13)
	ds_write2_b32 v107, v10, v11 offset1:1
	ds_write2_b32 v108, v12, v13 offset1:1
	s_waitcnt vmcnt(12)
	ds_write2_b32 v109, v14, v15 offset1:1
	ds_write2_b32 v110, v16, v17 offset1:1
	s_waitcnt vmcnt(11)
	ds_write2_b32 v111, v18, v19 offset1:1
	ds_write2_b32 v112, v20, v21 offset1:1
	s_waitcnt vmcnt(10)
	ds_write2_b32 v113, v22, v23 offset1:1
	ds_write2_b32 v114, v24, v25 offset1:1
	s_waitcnt vmcnt(9)
	ds_write2_b32 v115, v26, v27 offset1:1
	ds_write2_b32 v116, v28, v29 offset1:1
	s_waitcnt vmcnt(8)
	ds_write2_b32 v117, v30, v31 offset1:1
	ds_write2_b32 v118, v32, v33 offset1:1
	s_waitcnt vmcnt(7)
	ds_write2_b32 v119, v34, v35 offset1:1
	ds_write2_b32 v120, v36, v37 offset1:1
	s_waitcnt vmcnt(6)
	ds_write2_b32 v121, v38, v39 offset1:1
	ds_write2_b32 v122, v40, v41 offset1:1
	s_waitcnt vmcnt(5)
	ds_write2_b32 v123, v42, v43 offset1:1
	ds_write2_b32 v124, v44, v45 offset1:1
	s_waitcnt vmcnt(4)
	ds_write2_b32 v125, v46, v47 offset1:1
	ds_write2_b32 v126, v48, v49 offset1:1
	s_waitcnt vmcnt(3)
	ds_write2_b32 v72, v50, v51 offset1:1
	v_add_u32_e32 v2, 0x30c8, v69
	v_add_u32_e32 v26, 0x400, v77
	ds_write2_b32 v2, v52, v53 offset1:1
	v_add_u32_e32 v2, 0x34d0, v69
	v_lshlrev_b32_e32 v72, 1, v76
	s_waitcnt vmcnt(2)
; #define LAS __attribute__((address_space(3)))
; __device__ __forceinline__ unsigned pk2(float lo, float hi) { f32x2 v = {lo, hi}; bf16x2_t b = __builtin_convertvector(v, bf16x2_t); return __builtin_bit_cast(unsigned, b); }
; #define LDS_WAIT() asm volatile("s_waitcnt lgkmcnt(0)" ::: "memory")
; template <class MAP>
; __device__ __forceinline__ void transpose_item(const float* W, int ldw, int K, bf16_t* WT, int k0, int nd0, LAS float* scr, int lane, const MAP& map) {
;     ...
;     for (int i = 0; i < 16; ++i) { LAS float* d = scr + (4 * i + kr) * 65 + nq; d[0] = v[i].x; d[1] = v[i].y; d[2] = v[i].z; d[3] = v[i].w; }
;     LDS_WAIT(); asm volatile("" ::: "memory");
;     const int c = lane & 7;
; #pragma unroll
;     for (int j = 0; j < 8; ++j) { const int n = (lane >> 3) + 8 * j; const LAS float* s = scr + (8 * c) * 65 + n;
;         u32x4 o; o.x = pk2(s[0 * 65], s[1 * 65]); o.y = pk2(s[2 * 65], s[3 * 65]); o.z = pk2(s[4 * 65], s[5 * 65]); o.w = pk2(s[6 * 65], s[7 * 65]);
;         *(u32x4*)(WT + (size_t)(nd0 + n) * K + k0 + 8 * c) = o; }
;     LDS_WAIT(); asm volatile("" ::: "memory");
	ds_write2_b32 v2, v54, v55 offset1:1
	v_add_u32_e32 v2, 0x34d8, v69
	ds_write2_b32 v2, v56, v57 offset1:1
	v_add_u32_e32 v2, 0x38e0, v69
	s_waitcnt vmcnt(1)
	ds_write2_b32 v2, v58, v59 offset1:1
	v_add_u32_e32 v2, 0x38e8, v69
	ds_write2_b32 v2, v60, v61 offset1:1
	v_add_u32_e32 v2, 0x3cf0, v69
	s_waitcnt vmcnt(0)
	ds_write2_b32 v2, v62, v63 offset1:1
	v_add_u32_e32 v2, 0x3cf8, v69
	ds_write2_b32 v2, v64, v65 offset1:1
	s_waitcnt lgkmcnt(0)
	ds_read2_b32 v[6:7], v77 offset0:65 offset1:73
	ds_read2_b32 v[8:9], v77 offset1:8
	ds_read2_b32 v[10:11], v77 offset0:130 offset1:138
	ds_read2_b32 v[12:13], v77 offset0:195 offset1:203
	ds_read2_b32 v[14:15], v26 offset0:4 offset1:12
	ds_read2_b32 v[16:17], v26 offset0:69 offset1:77
	ds_read2_b32 v[18:19], v26 offset0:134 offset1:142
	ds_read2_b32 v[20:21], v26 offset0:199 offset1:207
	v_lshl_add_u64 v[22:23], s[62:63], 0, v[72:73]
	s_waitcnt lgkmcnt(6)
	v_cvt_pk_bf16_f32 v2, v8, v6
	v_or_b32_e32 v6, s4, v71
	v_lshlrev_b32_e32 v72, 11, v6
	s_waitcnt lgkmcnt(4)
	v_cvt_pk_bf16_f32 v3, v10, v12
	s_waitcnt lgkmcnt(2)
	v_cvt_pk_bf16_f32 v4, v14, v16
	s_waitcnt lgkmcnt(0)
	v_cvt_pk_bf16_f32 v5, v18, v20
	v_lshl_add_u64 v[24:25], v[22:23], 0, v[72:73]
	global_store_dwordx4 v[24:25], v[2:5], off nt
	v_or_b32_e32 v6, s4, v98
	v_lshlrev_b32_e32 v72, 11, v6
	v_cvt_pk_bf16_f32 v2, v9, v7
	v_cvt_pk_bf16_f32 v3, v11, v13
	v_cvt_pk_bf16_f32 v4, v15, v17
	v_cvt_pk_bf16_f32 v5, v19, v21
	ds_read2_b32 v[8:9], v77 offset0:81 offset1:89
	ds_read2_b32 v[10:11], v77 offset0:16 offset1:24
	ds_read2_b32 v[12:13], v77 offset0:146 offset1:154
	ds_read2_b32 v[14:15], v77 offset0:211 offset1:219
	ds_read2_b32 v[16:17], v26 offset0:20 offset1:28
	ds_read2_b32 v[18:19], v26 offset0:85 offset1:93
	ds_read2_b32 v[20:21], v26 offset0:150 offset1:158
	ds_read2_b32 v[24:25], v26 offset0:215 offset1:223
	v_lshl_add_u64 v[6:7], v[22:23], 0, v[72:73]
	global_store_dwordx4 v[6:7], v[2:5], off nt
	v_or_b32_e32 v6, s4, v99
	v_lshlrev_b32_e32 v72, 11, v6
	s_waitcnt lgkmcnt(6)
	v_cvt_pk_bf16_f32 v2, v10, v8
	s_waitcnt lgkmcnt(4)
	v_cvt_pk_bf16_f32 v3, v12, v14
	s_waitcnt lgkmcnt(2)
	v_cvt_pk_bf16_f32 v4, v16, v18
	s_waitcnt lgkmcnt(0)
	v_cvt_pk_bf16_f32 v5, v20, v24
	v_lshl_add_u64 v[6:7], v[22:23], 0, v[72:73]
	global_store_dwordx4 v[6:7], v[2:5], off nt
	v_or_b32_e32 v6, s4, v100
	v_lshlrev_b32_e32 v72, 11, v6
	v_cvt_pk_bf16_f32 v2, v11, v9
	v_cvt_pk_bf16_f32 v3, v13, v15
	v_cvt_pk_bf16_f32 v4, v17, v19
	v_cvt_pk_bf16_f32 v5, v21, v25
	ds_read2_b32 v[8:9], v77 offset0:32 offset1:40
	ds_read2_b32 v[10:11], v77 offset0:97 offset1:105
	ds_read2_b32 v[12:13], v77 offset0:162 offset1:170
	ds_read2_b32 v[14:15], v77 offset0:227 offset1:235
	ds_read2_b32 v[16:17], v26 offset0:36 offset1:44
	ds_read2_b32 v[18:19], v26 offset0:101 offset1:109
	ds_read2_b32 v[20:21], v26 offset0:166 offset1:174
	ds_read2_b32 v[24:25], v26 offset0:231 offset1:239
	v_lshl_add_u64 v[6:7], v[22:23], 0, v[72:73]
	global_store_dwordx4 v[6:7], v[2:5], off nt
	v_or_b32_e32 v6, s4, v101
	v_lshlrev_b32_e32 v72, 11, v6
	s_waitcnt lgkmcnt(6)
	v_cvt_pk_bf16_f32 v2, v8, v10
	s_waitcnt lgkmcnt(4)
	v_cvt_pk_bf16_f32 v3, v12, v14
	s_waitcnt lgkmcnt(2)
	v_cvt_pk_bf16_f32 v4, v16, v18
	s_waitcnt lgkmcnt(0)
	v_cvt_pk_bf16_f32 v5, v20, v24
	v_lshl_add_u64 v[6:7], v[22:23], 0, v[72:73]
	global_store_dwordx4 v[6:7], v[2:5], off nt
	v_or_b32_e32 v6, s4, v102
	v_lshlrev_b32_e32 v72, 11, v6
	v_cvt_pk_bf16_f32 v2, v9, v11
	v_cvt_pk_bf16_f32 v3, v13, v15
	v_cvt_pk_bf16_f32 v4, v17, v19
	v_cvt_pk_bf16_f32 v5, v21, v25
	ds_read2_b32 v[8:9], v77 offset0:48 offset1:56
	ds_read2_b32 v[10:11], v77 offset0:113 offset1:121
	ds_read2_b32 v[12:13], v77 offset0:178 offset1:186
	ds_read2_b32 v[14:15], v77 offset0:243 offset1:251
	ds_read2_b32 v[16:17], v26 offset0:52 offset1:60
	ds_read2_b32 v[18:19], v26 offset0:117 offset1:125
	ds_read2_b32 v[20:21], v26 offset0:182 offset1:190
	ds_read2_b32 v[24:25], v26 offset0:247 offset1:255
	v_lshl_add_u64 v[6:7], v[22:23], 0, v[72:73]
	global_store_dwordx4 v[6:7], v[2:5], off nt
	v_or_b32_e32 v6, s4, v103
	v_lshlrev_b32_e32 v72, 11, v6
	s_waitcnt lgkmcnt(6)
	v_cvt_pk_bf16_f32 v2, v8, v10
	s_waitcnt lgkmcnt(4)
	v_cvt_pk_bf16_f32 v3, v12, v14
	s_waitcnt lgkmcnt(2)
	v_cvt_pk_bf16_f32 v4, v16, v18
	s_waitcnt lgkmcnt(0)
	v_cvt_pk_bf16_f32 v5, v20, v24
	v_lshl_add_u64 v[6:7], v[22:23], 0, v[72:73]
	global_store_dwordx4 v[6:7], v[2:5], off nt
	v_or_b32_e32 v6, s4, v104
	v_lshlrev_b32_e32 v72, 11, v6
	v_cvt_pk_bf16_f32 v2, v9, v11
	v_cvt_pk_bf16_f32 v3, v13, v15
	v_cvt_pk_bf16_f32 v4, v17, v19
	v_cvt_pk_bf16_f32 v5, v21, v25
	v_lshl_add_u64 v[6:7], v[22:23], 0, v[72:73]
	global_store_dwordx4 v[6:7], v[2:5], off nt
	s_waitcnt lgkmcnt(0)
